# phase 3 compress-MLP tiles: hand-written epilogue, gelu_tanh as x*rcp(1+exp2(.)) in fp32 (identity 0.5(1+tanh u)=sigmoid(2u)) instead of libm tanhf expansion
# speedup vs baseline: 1.0001x; 1.0001x over previous
.LBB0_1305:
	v_readlane_b32 s0, v252, 30
	v_readlane_b32 s1, v252, 31
	v_readlane_b32 s80, v254, 19
	v_readlane_b32 s74, v254, 25
	s_andn2_b64 vcc, exec, s[0:1]
	v_readlane_b32 s81, v254, 20
	v_readlane_b32 s75, v254, 26
	s_mov_b32 s25, 0x8000
	s_movk_i32 s34, 0x3fff
	s_cbranch_vccnz .LBB0_1574
	s_add_u32 s12, s16, 0x5800000
	s_addc_u32 s13, s17, 0
	s_add_u32 s14, s16, 0xe000000
	s_addc_u32 s15, s17, 0
	s_add_u32 s2, s16, 0xe280000
	v_lshlrev_b32_e32 v192, 2, v56
	v_readlane_b32 s4, v254, 10
	s_addc_u32 s3, s17, 0
	v_or_b32_e32 v195, 1, v192
	v_or_b32_e32 v210, 2, v192
	v_or_b32_e32 v211, 3, v192
	v_or_b32_e32 v212, 8, v192
	v_or_b32_e32 v213, 9, v192
	v_or_b32_e32 v214, 10, v192
	v_or_b32_e32 v215, 11, v192
	v_or_b32_e32 v216, 16, v192
	v_or_b32_e32 v217, 17, v192
	v_or_b32_e32 v218, 18, v192
	v_or_b32_e32 v219, 19, v192
	v_or_b32_e32 v220, 24, v192
	v_or_b32_e32 v221, 25, v192
	v_or_b32_e32 v222, 26, v192
	v_or_b32_e32 v223, 27, v192
	v_or_b32_e32 v224, 32, v192
	v_or_b32_e32 v225, 33, v192
	v_or_b32_e32 v226, 34, v192
	v_or_b32_e32 v227, 35, v192
	v_or_b32_e32 v228, 40, v192
	v_or_b32_e32 v229, 41, v192
	v_or_b32_e32 v230, 42, v192
	v_or_b32_e32 v231, 43, v192
	v_or_b32_e32 v232, 48, v192
	v_or_b32_e32 v233, 49, v192
	v_or_b32_e32 v234, 50, v192
	v_or_b32_e32 v235, 51, v192
	v_or_b32_e32 v236, 56, v192
	v_or_b32_e32 v237, 57, v192
	v_or_b32_e32 v238, 58, v192
	v_or_b32_e32 v239, 59, v192
	v_lshl_or_b32 v240, v54, 6, v55
	v_readlane_b32 s5, v254, 11
	v_readlane_b32 s18, v251, 24
	s_branch .LBB0_1308
.LBB0_1308:
	s_ashr_i32 s6, s18, 5
	s_bfe_u32 s19, s18, 0x40001
	s_ashr_i32 s7, s6, 31
	s_lshl_b32 s8, s19, 18
	s_and_b32 s20, s18, 1
	s_lshl_b64 s[0:1], s[6:7], 22
	s_add_u32 s9, s12, s0
	s_addc_u32 s11, s13, s1
	s_add_u32 s10, s9, s8
	s_addc_u32 s11, s11, 0
	v_cndmask_b32_e64 v0, 0, 1, s[4:5]
	s_cmp_lt_u32 s18, 32
	s_mov_b32 s9, 0x540000
	v_lshlrev_b32_e32 v1, 19, v0
	v_mov_b32_e32 v0, v161
	s_cselect_b32 s9, s9, 0x640000
	v_mov_b32_e32 v17, v186
	s_add_u32 s22, s16, s9
	s_addc_u32 s23, s17, 0
	v_lshlrev_b32_e32 v2, 4, v17
	s_lshl_b32 s24, s20, 19
	v_ashrrev_i32_e32 v18, 3, v17
	v_and_b32_e32 v16, 0x70, v2
	s_add_u32 s22, s22, s24
	v_lshl_or_b32 v160, v18, 11, v16
	v_lshl_or_b32 v6, v18, 12, v16
	s_addc_u32 s23, s23, 0
	v_add_u32_e32 v2, 0x10000, v160
	v_add_u32_e32 v4, 0x20000, v160
	s_waitcnt vmcnt(0)
	v_add_u32_e32 v8, 0x30000, v160
	v_add_u32_e32 v10, 0x20000, v6
	v_add_u32_e32 v12, 0x40000, v6
	s_barrier
	global_load_dwordx4 v[64:67], v160, s[10:11]
	global_load_dwordx4 v[68:71], v2, s[10:11]
	global_load_dwordx4 v[72:75], v4, s[10:11]
	global_load_dwordx4 v[76:79], v8, s[10:11]
	global_load_dwordx4 v[80:83], v6, s[22:23]
	global_load_dwordx4 v[92:95], v10, s[22:23]
	global_load_dwordx4 v[100:103], v12, s[22:23]
	v_add_u32_e32 v14, 0x60000, v6
	global_load_dwordx4 v[112:115], v14, s[22:23]
	global_load_dwordx4 v[84:87], v160, s[10:11] offset:128
	global_load_dwordx4 v[88:91], v2, s[10:11] offset:128
	global_load_dwordx4 v[96:99], v4, s[10:11] offset:128
	global_load_dwordx4 v[104:107], v8, s[10:11] offset:128
	global_load_dwordx4 v[108:111], v6, s[22:23] offset:128
	global_load_dwordx4 v[116:119], v10, s[22:23] offset:128
	global_load_dwordx4 v[120:123], v12, s[22:23] offset:128
	global_load_dwordx4 v[124:127], v14, s[22:23] offset:128
	v_mad_u64_u32 v[164:165], s[10:11], v18, s43, v[16:17]
	v_and_b32_e32 v18, 0x5f, v17
	v_lshrrev_b32_e32 v19, 1, v17
	v_and_b32_e32 v17, 31, v17
	v_and_b32_e32 v16, 16, v19
	v_and_or_b32 v17, v19, s44, v17
	v_mov_b32_e32 v3, v161
	v_mov_b32_e32 v5, v161
	v_mov_b32_e32 v9, v161
	v_mov_b32_e32 v7, v161
	v_mov_b32_e32 v11, v161
	v_mov_b32_e32 v13, v161
	v_mov_b32_e32 v15, v161
	v_mad_u32_u24 v165, v18, s43, v16
	v_mad_u64_u32 v[166:167], s[10:11], v17, s43, v[16:17]
	v_or_b32_e32 v16, s9, v1
	v_mov_b32_e32 v17, v161
	s_or_b32 s0, s0, s8
	s_mov_b32 s21, 0
	v_add_u32_e32 v167, 0xd800, v164
	v_lshl_add_u64 v[168:169], v[16:17], 0, v[14:15]
	v_lshl_add_u64 v[170:171], v[16:17], 0, v[12:13]
	v_lshl_add_u64 v[172:173], v[16:17], 0, v[10:11]
	v_lshl_add_u64 v[174:175], v[16:17], 0, v[6:7]
	v_lshl_add_u64 v[176:177], s[0:1], 0, v[8:9]
	v_lshl_add_u64 v[178:179], s[0:1], 0, v[4:5]
	v_lshl_add_u64 v[180:181], s[0:1], 0, v[2:3]
	v_lshl_add_u64 v[182:183], s[0:1], 0, v[160:161]
	v_mov_b32_e32 v1, v0
	v_mov_b32_e32 v2, v0
	v_mov_b32_e32 v3, v0
	v_mov_b32_e32 v4, v0
	v_mov_b32_e32 v5, v0
	v_mov_b32_e32 v6, v0
	v_mov_b32_e32 v7, v0
	v_mov_b32_e32 v8, v0
	v_mov_b32_e32 v9, v0
	v_mov_b32_e32 v10, v0
	v_mov_b32_e32 v11, v0
	v_mov_b32_e32 v12, v0
	v_mov_b32_e32 v13, v0
	v_mov_b32_e32 v14, v0
	v_mov_b32_e32 v15, v0
	v_mov_b32_e32 v16, v0
	v_mov_b32_e32 v17, v0
	v_mov_b32_e32 v18, v0
	v_mov_b32_e32 v19, v0
	v_mov_b32_e32 v20, v0
	v_mov_b32_e32 v21, v0
	v_mov_b32_e32 v22, v0
	v_mov_b32_e32 v23, v0
	v_mov_b32_e32 v24, v0
	v_mov_b32_e32 v25, v0
	v_mov_b32_e32 v26, v0
	v_mov_b32_e32 v27, v0
	v_mov_b32_e32 v28, v0
	v_mov_b32_e32 v29, v0
	v_mov_b32_e32 v30, v0
	v_mov_b32_e32 v31, v0
	v_mov_b32_e32 v32, v0
	v_mov_b32_e32 v33, v0
	v_mov_b32_e32 v34, v0
	v_mov_b32_e32 v35, v0
	v_mov_b32_e32 v36, v0
	v_mov_b32_e32 v37, v0
	v_mov_b32_e32 v38, v0
	v_mov_b32_e32 v39, v0
	v_mov_b32_e32 v40, v0
	v_mov_b32_e32 v41, v0
	v_mov_b32_e32 v42, v0
	v_mov_b32_e32 v43, v0
	v_mov_b32_e32 v44, v0
	v_mov_b32_e32 v45, v0
	v_mov_b32_e32 v46, v0
	v_mov_b32_e32 v47, v0
	v_mov_b32_e32 v48, v0
	v_mov_b32_e32 v49, v0
	v_mov_b32_e32 v50, v0
	v_mov_b32_e32 v51, v0
	v_mov_b32_e32 v52, v0
	v_mov_b32_e32 v53, v0
	v_mov_b32_e32 v54, v0
	v_mov_b32_e32 v55, v0
	v_mov_b32_e32 v56, v0
	v_mov_b32_e32 v57, v0
	v_mov_b32_e32 v58, v0
	v_mov_b32_e32 v59, v0
	v_mov_b32_e32 v60, v0
	v_mov_b32_e32 v61, v0
	v_mov_b32_e32 v62, v0
	v_mov_b32_e32 v63, v0
	s_waitcnt vmcnt(15)
	ds_write_b128 v164, v[64:67]
	s_waitcnt vmcnt(14)
	ds_write_b128 v164, v[68:71] offset:4608
	s_waitcnt vmcnt(13)
	ds_write_b128 v164, v[72:75] offset:9216
	s_waitcnt vmcnt(12)
	ds_write_b128 v164, v[76:79] offset:13824
	s_waitcnt vmcnt(11)
	ds_write_b128 v164, v[80:83] offset:36864
	s_waitcnt vmcnt(10)
	ds_write_b128 v164, v[92:95] offset:41472
	s_waitcnt vmcnt(9)
	ds_write_b128 v164, v[100:103] offset:46080
	s_waitcnt vmcnt(8)
	ds_write_b128 v164, v[112:115] offset:50688
	s_waitcnt lgkmcnt(0)
	s_barrier
	s_branch .LBB0_1310

.LBB0_1318:
	v_readfirstlane_b32 s8, v186
	v_and_b32_e32 v64, 63, v186
	v_and_b32_e32 v65, 31, v64
	v_lshrrev_b32_e32 v66, 5, v64
	s_lshr_b32 s8, s8, 6
	s_and_b32 s9, s8, 1
	s_lshr_b32 s8, s8, 1
	s_lshl_b32 s8, s8, 6
	s_lshl_b32 s10, s20, 7
	s_lshl_b32 s9, s9, 6
	s_add_i32 s9, s9, s10
	v_add_u32_e32 v67, s9, v65
	s_lshl_b32 s10, s6, 8
	v_add_u32_e32 v68, s10, v67
	v_lshlrev_b32_e32 v68, 2, v68
	global_load_dword v70, v68, s[2:3]
	global_load_dword v71, v68, s[2:3] offset:128
	s_lshl_b32 s10, s19, 7
	s_add_i32 s8, s8, s10
	v_lshl_add_u32 v69, v66, 2, s8
	v_lshlrev_b32_e32 v69, 8, v69
	v_add_u32_e32 v69, v67, v69
	v_lshlrev_b32_e32 v69, 1, v69
	s_lshl_b32 s10, s6, 20
	s_add_u32 s22, s14, s10
	s_addc_u32 s23, s15, 0
	v_mov_b32_e32 v72, 0xc0135761
	v_mov_b32_e32 v73, 0xbdd2d3e8
	s_waitcnt vmcnt(0)
	v_add_f32_e32 v48, v48, v70
	v_add_f32_e32 v32, v32, v71
	v_add_f32_e32 v49, v49, v70
	v_add_f32_e32 v33, v33, v71
	v_mul_f32_e32 v74, v48, v48
	v_mul_f32_e32 v75, v32, v32
	v_mul_f32_e32 v76, v49, v49
	v_mul_f32_e32 v77, v33, v33
	v_fma_f32 v74, v74, v73, v72
	v_fma_f32 v75, v75, v73, v72
	v_fma_f32 v76, v76, v73, v72
	v_fma_f32 v77, v77, v73, v72
	v_mul_f32_e32 v74, v74, v48
	v_mul_f32_e32 v75, v75, v32
	v_mul_f32_e32 v76, v76, v49
	v_mul_f32_e32 v77, v77, v33
	v_exp_f32_e32 v74, v74
	v_exp_f32_e32 v75, v75
	v_exp_f32_e32 v76, v76
	v_exp_f32_e32 v77, v77
	v_add_f32_e32 v74, 1.0, v74
	v_add_f32_e32 v75, 1.0, v75
	v_add_f32_e32 v76, 1.0, v76
	v_add_f32_e32 v77, 1.0, v77
	v_rcp_f32_e32 v74, v74
	v_rcp_f32_e32 v75, v75
	v_rcp_f32_e32 v76, v76
	v_rcp_f32_e32 v77, v77
	v_mul_f32_e32 v74, v48, v74
	v_mul_f32_e32 v75, v32, v75
	v_mul_f32_e32 v76, v49, v76
	v_mul_f32_e32 v77, v33, v77
	v_cvt_pk_bf16_f32 v74, v74, v74
	v_cvt_pk_bf16_f32 v75, v75, v75
	v_cvt_pk_bf16_f32 v76, v76, v76
	v_cvt_pk_bf16_f32 v77, v77, v77
	v_mov_b32_e32 v78, v69
	global_store_short v78, v74, s[22:23]
	global_store_short v78, v75, s[22:23] offset:64
	v_add_u32_e32 v79, 0x200, v69
	global_store_short v79, v76, s[22:23]
	global_store_short v79, v77, s[22:23] offset:64
	v_add_f32_e32 v50, v50, v70
	v_add_f32_e32 v34, v34, v71
	v_add_f32_e32 v51, v51, v70
	v_add_f32_e32 v35, v35, v71
	v_mul_f32_e32 v74, v50, v50
	v_mul_f32_e32 v75, v34, v34
	v_mul_f32_e32 v76, v51, v51
	v_mul_f32_e32 v77, v35, v35
	v_fma_f32 v74, v74, v73, v72
	v_fma_f32 v75, v75, v73, v72
	v_fma_f32 v76, v76, v73, v72
	v_fma_f32 v77, v77, v73, v72
	v_mul_f32_e32 v74, v74, v50
	v_mul_f32_e32 v75, v75, v34
	v_mul_f32_e32 v76, v76, v51
	v_mul_f32_e32 v77, v77, v35
	v_exp_f32_e32 v74, v74
	v_exp_f32_e32 v75, v75
	v_exp_f32_e32 v76, v76
	v_exp_f32_e32 v77, v77
	v_add_f32_e32 v74, 1.0, v74
	v_add_f32_e32 v75, 1.0, v75
	v_add_f32_e32 v76, 1.0, v76
	v_add_f32_e32 v77, 1.0, v77
	v_rcp_f32_e32 v74, v74
	v_rcp_f32_e32 v75, v75
	v_rcp_f32_e32 v76, v76
	v_rcp_f32_e32 v77, v77
	v_mul_f32_e32 v74, v50, v74
	v_mul_f32_e32 v75, v34, v75
	v_mul_f32_e32 v76, v51, v76
	v_mul_f32_e32 v77, v35, v77
	v_cvt_pk_bf16_f32 v74, v74, v74
	v_cvt_pk_bf16_f32 v75, v75, v75
	v_cvt_pk_bf16_f32 v76, v76, v76
	v_cvt_pk_bf16_f32 v77, v77, v77
	v_add_u32_e32 v78, 0x400, v69
	global_store_short v78, v74, s[22:23]
	global_store_short v78, v75, s[22:23] offset:64
	v_add_u32_e32 v79, 0x600, v69
	global_store_short v79, v76, s[22:23]
	global_store_short v79, v77, s[22:23] offset:64
	v_add_f32_e32 v52, v52, v70
	v_add_f32_e32 v36, v36, v71
	v_add_f32_e32 v53, v53, v70
	v_add_f32_e32 v37, v37, v71
	v_mul_f32_e32 v74, v52, v52
	v_mul_f32_e32 v75, v36, v36
	v_mul_f32_e32 v76, v53, v53
	v_mul_f32_e32 v77, v37, v37
	v_fma_f32 v74, v74, v73, v72
	v_fma_f32 v75, v75, v73, v72
	v_fma_f32 v76, v76, v73, v72
	v_fma_f32 v77, v77, v73, v72
	v_mul_f32_e32 v74, v74, v52
	v_mul_f32_e32 v75, v75, v36
	v_mul_f32_e32 v76, v76, v53
	v_mul_f32_e32 v77, v77, v37
	v_exp_f32_e32 v74, v74
	v_exp_f32_e32 v75, v75
	v_exp_f32_e32 v76, v76
	v_exp_f32_e32 v77, v77
	v_add_f32_e32 v74, 1.0, v74
	v_add_f32_e32 v75, 1.0, v75
	v_add_f32_e32 v76, 1.0, v76
	v_add_f32_e32 v77, 1.0, v77
	v_rcp_f32_e32 v74, v74
	v_rcp_f32_e32 v75, v75
	v_rcp_f32_e32 v76, v76
	v_rcp_f32_e32 v77, v77
	v_mul_f32_e32 v74, v52, v74
	v_mul_f32_e32 v75, v36, v75
	v_mul_f32_e32 v76, v53, v76
	v_mul_f32_e32 v77, v37, v77
	v_cvt_pk_bf16_f32 v74, v74, v74
	v_cvt_pk_bf16_f32 v75, v75, v75
	v_cvt_pk_bf16_f32 v76, v76, v76
	v_cvt_pk_bf16_f32 v77, v77, v77
	v_add_u32_e32 v78, 0x1000, v69
	global_store_short v78, v74, s[22:23]
	global_store_short v78, v75, s[22:23] offset:64
	v_add_u32_e32 v79, 0x1200, v69
	global_store_short v79, v76, s[22:23]
	global_store_short v79, v77, s[22:23] offset:64
	v_add_f32_e32 v54, v54, v70
	v_add_f32_e32 v38, v38, v71
	v_add_f32_e32 v55, v55, v70
	v_add_f32_e32 v39, v39, v71
	v_mul_f32_e32 v74, v54, v54
	v_mul_f32_e32 v75, v38, v38
	v_mul_f32_e32 v76, v55, v55
	v_mul_f32_e32 v77, v39, v39
	v_fma_f32 v74, v74, v73, v72
	v_fma_f32 v75, v75, v73, v72
	v_fma_f32 v76, v76, v73, v72
	v_fma_f32 v77, v77, v73, v72
	v_mul_f32_e32 v74, v74, v54
	v_mul_f32_e32 v75, v75, v38
	v_mul_f32_e32 v76, v76, v55
	v_mul_f32_e32 v77, v77, v39
	v_exp_f32_e32 v74, v74
	v_exp_f32_e32 v75, v75
	v_exp_f32_e32 v76, v76
	v_exp_f32_e32 v77, v77
	v_add_f32_e32 v74, 1.0, v74
	v_add_f32_e32 v75, 1.0, v75
	v_add_f32_e32 v76, 1.0, v76
	v_add_f32_e32 v77, 1.0, v77
	v_rcp_f32_e32 v74, v74
	v_rcp_f32_e32 v75, v75
	v_rcp_f32_e32 v76, v76
	v_rcp_f32_e32 v77, v77
	v_mul_f32_e32 v74, v54, v74
	v_mul_f32_e32 v75, v38, v75
	v_mul_f32_e32 v76, v55, v76
	v_mul_f32_e32 v77, v39, v77
	v_cvt_pk_bf16_f32 v74, v74, v74
	v_cvt_pk_bf16_f32 v75, v75, v75
	v_cvt_pk_bf16_f32 v76, v76, v76
	v_cvt_pk_bf16_f32 v77, v77, v77
	v_add_u32_e32 v78, 0x1400, v69
	global_store_short v78, v74, s[22:23]
	global_store_short v78, v75, s[22:23] offset:64
	v_add_u32_e32 v79, 0x1600, v69
	global_store_short v79, v76, s[22:23]
	global_store_short v79, v77, s[22:23] offset:64
	v_add_f32_e32 v56, v56, v70
	v_add_f32_e32 v40, v40, v71
	v_add_f32_e32 v57, v57, v70
	v_add_f32_e32 v41, v41, v71
	v_mul_f32_e32 v74, v56, v56
	v_mul_f32_e32 v75, v40, v40
	v_mul_f32_e32 v76, v57, v57
	v_mul_f32_e32 v77, v41, v41
	v_fma_f32 v74, v74, v73, v72
	v_fma_f32 v75, v75, v73, v72
	v_fma_f32 v76, v76, v73, v72
	v_fma_f32 v77, v77, v73, v72
	v_mul_f32_e32 v74, v74, v56
	v_mul_f32_e32 v75, v75, v40
	v_mul_f32_e32 v76, v76, v57
	v_mul_f32_e32 v77, v77, v41
	v_exp_f32_e32 v74, v74
	v_exp_f32_e32 v75, v75
	v_exp_f32_e32 v76, v76
	v_exp_f32_e32 v77, v77
	v_add_f32_e32 v74, 1.0, v74
	v_add_f32_e32 v75, 1.0, v75
	v_add_f32_e32 v76, 1.0, v76
	v_add_f32_e32 v77, 1.0, v77
	v_rcp_f32_e32 v74, v74
	v_rcp_f32_e32 v75, v75
	v_rcp_f32_e32 v76, v76
	v_rcp_f32_e32 v77, v77
	v_mul_f32_e32 v74, v56, v74
	v_mul_f32_e32 v75, v40, v75
	v_mul_f32_e32 v76, v57, v76
	v_mul_f32_e32 v77, v41, v77
	v_cvt_pk_bf16_f32 v74, v74, v74
	v_cvt_pk_bf16_f32 v75, v75, v75
	v_cvt_pk_bf16_f32 v76, v76, v76
	v_cvt_pk_bf16_f32 v77, v77, v77
	v_add_u32_e32 v78, 0x2000, v69
	global_store_short v78, v74, s[22:23]
	global_store_short v78, v75, s[22:23] offset:64
	v_add_u32_e32 v79, 0x2200, v69
	global_store_short v79, v76, s[22:23]
	global_store_short v79, v77, s[22:23] offset:64
	v_add_f32_e32 v58, v58, v70
	v_add_f32_e32 v42, v42, v71
	v_add_f32_e32 v59, v59, v70
	v_add_f32_e32 v43, v43, v71
	v_mul_f32_e32 v74, v58, v58
	v_mul_f32_e32 v75, v42, v42
	v_mul_f32_e32 v76, v59, v59
	v_mul_f32_e32 v77, v43, v43
	v_fma_f32 v74, v74, v73, v72
	v_fma_f32 v75, v75, v73, v72
	v_fma_f32 v76, v76, v73, v72
	v_fma_f32 v77, v77, v73, v72
	v_mul_f32_e32 v74, v74, v58
	v_mul_f32_e32 v75, v75, v42
	v_mul_f32_e32 v76, v76, v59
	v_mul_f32_e32 v77, v77, v43
	v_exp_f32_e32 v74, v74
	v_exp_f32_e32 v75, v75
	v_exp_f32_e32 v76, v76
	v_exp_f32_e32 v77, v77
	v_add_f32_e32 v74, 1.0, v74
	v_add_f32_e32 v75, 1.0, v75
	v_add_f32_e32 v76, 1.0, v76
	v_add_f32_e32 v77, 1.0, v77
	v_rcp_f32_e32 v74, v74
	v_rcp_f32_e32 v75, v75
	v_rcp_f32_e32 v76, v76
	v_rcp_f32_e32 v77, v77
	v_mul_f32_e32 v74, v58, v74
	v_mul_f32_e32 v75, v42, v75
	v_mul_f32_e32 v76, v59, v76
	v_mul_f32_e32 v77, v43, v77
	v_cvt_pk_bf16_f32 v74, v74, v74
	v_cvt_pk_bf16_f32 v75, v75, v75
	v_cvt_pk_bf16_f32 v76, v76, v76
	v_cvt_pk_bf16_f32 v77, v77, v77
	v_add_u32_e32 v78, 0x2400, v69
	global_store_short v78, v74, s[22:23]
	global_store_short v78, v75, s[22:23] offset:64
	v_add_u32_e32 v79, 0x2600, v69
	global_store_short v79, v76, s[22:23]
	global_store_short v79, v77, s[22:23] offset:64
	v_add_f32_e32 v60, v60, v70
	v_add_f32_e32 v44, v44, v71
	v_add_f32_e32 v61, v61, v70
	v_add_f32_e32 v45, v45, v71
	v_mul_f32_e32 v74, v60, v60
	v_mul_f32_e32 v75, v44, v44
	v_mul_f32_e32 v76, v61, v61
	v_mul_f32_e32 v77, v45, v45
	v_fma_f32 v74, v74, v73, v72
	v_fma_f32 v75, v75, v73, v72
	v_fma_f32 v76, v76, v73, v72
	v_fma_f32 v77, v77, v73, v72
	v_mul_f32_e32 v74, v74, v60
	v_mul_f32_e32 v75, v75, v44
	v_mul_f32_e32 v76, v76, v61
	v_mul_f32_e32 v77, v77, v45
	v_exp_f32_e32 v74, v74
	v_exp_f32_e32 v75, v75
	v_exp_f32_e32 v76, v76
	v_exp_f32_e32 v77, v77
	v_add_f32_e32 v74, 1.0, v74
	v_add_f32_e32 v75, 1.0, v75
	v_add_f32_e32 v76, 1.0, v76
	v_add_f32_e32 v77, 1.0, v77
	v_rcp_f32_e32 v74, v74
	v_rcp_f32_e32 v75, v75
	v_rcp_f32_e32 v76, v76
	v_rcp_f32_e32 v77, v77
	v_mul_f32_e32 v74, v60, v74
	v_mul_f32_e32 v75, v44, v75
	v_mul_f32_e32 v76, v61, v76
	v_mul_f32_e32 v77, v45, v77
	v_cvt_pk_bf16_f32 v74, v74, v74
	v_cvt_pk_bf16_f32 v75, v75, v75
	v_cvt_pk_bf16_f32 v76, v76, v76
	v_cvt_pk_bf16_f32 v77, v77, v77
	v_add_u32_e32 v78, 0x3000, v69
	global_store_short v78, v74, s[22:23]
	global_store_short v78, v75, s[22:23] offset:64
	v_add_u32_e32 v79, 0x3200, v69
	global_store_short v79, v76, s[22:23]
	global_store_short v79, v77, s[22:23] offset:64
	v_add_f32_e32 v62, v62, v70
	v_add_f32_e32 v46, v46, v71
	v_add_f32_e32 v63, v63, v70
	v_add_f32_e32 v47, v47, v71
	v_mul_f32_e32 v74, v62, v62
	v_mul_f32_e32 v75, v46, v46
	v_mul_f32_e32 v76, v63, v63
	v_mul_f32_e32 v77, v47, v47
	v_fma_f32 v74, v74, v73, v72
	v_fma_f32 v75, v75, v73, v72
	v_fma_f32 v76, v76, v73, v72
	v_fma_f32 v77, v77, v73, v72
	v_mul_f32_e32 v74, v74, v62
	v_mul_f32_e32 v75, v75, v46
	v_mul_f32_e32 v76, v76, v63
	v_mul_f32_e32 v77, v77, v47
	v_exp_f32_e32 v74, v74
	v_exp_f32_e32 v75, v75
	v_exp_f32_e32 v76, v76
	v_exp_f32_e32 v77, v77
	v_add_f32_e32 v74, 1.0, v74
	v_add_f32_e32 v75, 1.0, v75
	v_add_f32_e32 v76, 1.0, v76
	v_add_f32_e32 v77, 1.0, v77
	v_rcp_f32_e32 v74, v74
	v_rcp_f32_e32 v75, v75
	v_rcp_f32_e32 v76, v76
	v_rcp_f32_e32 v77, v77
	v_mul_f32_e32 v74, v62, v74
	v_mul_f32_e32 v75, v46, v75
	v_mul_f32_e32 v76, v63, v76
	v_mul_f32_e32 v77, v47, v77
	v_cvt_pk_bf16_f32 v74, v74, v74
	v_cvt_pk_bf16_f32 v75, v75, v75
	v_cvt_pk_bf16_f32 v76, v76, v76
	v_cvt_pk_bf16_f32 v77, v77, v77
	v_add_u32_e32 v78, 0x3400, v69
	global_store_short v78, v74, s[22:23]
	global_store_short v78, v75, s[22:23] offset:64
	v_add_u32_e32 v79, 0x3600, v69
	global_store_short v79, v76, s[22:23]
	global_store_short v79, v77, s[22:23] offset:64
	v_add_f32_e32 v16, v16, v70
	v_add_f32_e32 v0, v0, v71
	v_add_f32_e32 v17, v17, v70
	v_add_f32_e32 v1, v1, v71
	v_mul_f32_e32 v74, v16, v16
	v_mul_f32_e32 v75, v0, v0
	v_mul_f32_e32 v76, v17, v17
	v_mul_f32_e32 v77, v1, v1
	v_fma_f32 v74, v74, v73, v72
	v_fma_f32 v75, v75, v73, v72
	v_fma_f32 v76, v76, v73, v72
	v_fma_f32 v77, v77, v73, v72
	v_mul_f32_e32 v74, v74, v16
	v_mul_f32_e32 v75, v75, v0
	v_mul_f32_e32 v76, v76, v17
	v_mul_f32_e32 v77, v77, v1
	v_exp_f32_e32 v74, v74
	v_exp_f32_e32 v75, v75
	v_exp_f32_e32 v76, v76
	v_exp_f32_e32 v77, v77
	v_add_f32_e32 v74, 1.0, v74
	v_add_f32_e32 v75, 1.0, v75
	v_add_f32_e32 v76, 1.0, v76
	v_add_f32_e32 v77, 1.0, v77
	v_rcp_f32_e32 v74, v74
	v_rcp_f32_e32 v75, v75
	v_rcp_f32_e32 v76, v76
	v_rcp_f32_e32 v77, v77
	v_mul_f32_e32 v74, v16, v74
	v_mul_f32_e32 v75, v0, v75
	v_mul_f32_e32 v76, v17, v76
	v_mul_f32_e32 v77, v1, v77
	v_cvt_pk_bf16_f32 v74, v74, v74
	v_cvt_pk_bf16_f32 v75, v75, v75
	v_cvt_pk_bf16_f32 v76, v76, v76
	v_cvt_pk_bf16_f32 v77, v77, v77
	v_add_u32_e32 v78, 0x4000, v69
	global_store_short v78, v74, s[22:23]
	global_store_short v78, v75, s[22:23] offset:64
	v_add_u32_e32 v79, 0x4200, v69
	global_store_short v79, v76, s[22:23]
	global_store_short v79, v77, s[22:23] offset:64
	v_add_f32_e32 v18, v18, v70
	v_add_f32_e32 v2, v2, v71
	v_add_f32_e32 v19, v19, v70
	v_add_f32_e32 v3, v3, v71
	v_mul_f32_e32 v74, v18, v18
	v_mul_f32_e32 v75, v2, v2
	v_mul_f32_e32 v76, v19, v19
	v_mul_f32_e32 v77, v3, v3
	v_fma_f32 v74, v74, v73, v72
	v_fma_f32 v75, v75, v73, v72
	v_fma_f32 v76, v76, v73, v72
	v_fma_f32 v77, v77, v73, v72
	v_mul_f32_e32 v74, v74, v18
	v_mul_f32_e32 v75, v75, v2
	v_mul_f32_e32 v76, v76, v19
	v_mul_f32_e32 v77, v77, v3
	v_exp_f32_e32 v74, v74
	v_exp_f32_e32 v75, v75
	v_exp_f32_e32 v76, v76
	v_exp_f32_e32 v77, v77
	v_add_f32_e32 v74, 1.0, v74
	v_add_f32_e32 v75, 1.0, v75
	v_add_f32_e32 v76, 1.0, v76
	v_add_f32_e32 v77, 1.0, v77
	v_rcp_f32_e32 v74, v74
	v_rcp_f32_e32 v75, v75
	v_rcp_f32_e32 v76, v76
	v_rcp_f32_e32 v77, v77
	v_mul_f32_e32 v74, v18, v74
	v_mul_f32_e32 v75, v2, v75
	v_mul_f32_e32 v76, v19, v76
	v_mul_f32_e32 v77, v3, v77
	v_cvt_pk_bf16_f32 v74, v74, v74
	v_cvt_pk_bf16_f32 v75, v75, v75
	v_cvt_pk_bf16_f32 v76, v76, v76
	v_cvt_pk_bf16_f32 v77, v77, v77
	v_add_u32_e32 v78, 0x4400, v69
	global_store_short v78, v74, s[22:23]
	global_store_short v78, v75, s[22:23] offset:64
	v_add_u32_e32 v79, 0x4600, v69
	global_store_short v79, v76, s[22:23]
	global_store_short v79, v77, s[22:23] offset:64
	v_add_f32_e32 v20, v20, v70
	v_add_f32_e32 v4, v4, v71
	v_add_f32_e32 v21, v21, v70
	v_add_f32_e32 v5, v5, v71
	v_mul_f32_e32 v74, v20, v20
	v_mul_f32_e32 v75, v4, v4
	v_mul_f32_e32 v76, v21, v21
	v_mul_f32_e32 v77, v5, v5
	v_fma_f32 v74, v74, v73, v72
	v_fma_f32 v75, v75, v73, v72
	v_fma_f32 v76, v76, v73, v72
	v_fma_f32 v77, v77, v73, v72
	v_mul_f32_e32 v74, v74, v20
	v_mul_f32_e32 v75, v75, v4
	v_mul_f32_e32 v76, v76, v21
	v_mul_f32_e32 v77, v77, v5
	v_exp_f32_e32 v74, v74
	v_exp_f32_e32 v75, v75
	v_exp_f32_e32 v76, v76
	v_exp_f32_e32 v77, v77
	v_add_f32_e32 v74, 1.0, v74
	v_add_f32_e32 v75, 1.0, v75
	v_add_f32_e32 v76, 1.0, v76
	v_add_f32_e32 v77, 1.0, v77
	v_rcp_f32_e32 v74, v74
	v_rcp_f32_e32 v75, v75
	v_rcp_f32_e32 v76, v76
	v_rcp_f32_e32 v77, v77
	v_mul_f32_e32 v74, v20, v74
	v_mul_f32_e32 v75, v4, v75
	v_mul_f32_e32 v76, v21, v76
	v_mul_f32_e32 v77, v5, v77
	v_cvt_pk_bf16_f32 v74, v74, v74
	v_cvt_pk_bf16_f32 v75, v75, v75
	v_cvt_pk_bf16_f32 v76, v76, v76
	v_cvt_pk_bf16_f32 v77, v77, v77
	v_add_u32_e32 v78, 0x5000, v69
	global_store_short v78, v74, s[22:23]
	global_store_short v78, v75, s[22:23] offset:64
	v_add_u32_e32 v79, 0x5200, v69
	global_store_short v79, v76, s[22:23]
	global_store_short v79, v77, s[22:23] offset:64
	v_add_f32_e32 v22, v22, v70
	v_add_f32_e32 v6, v6, v71
	v_add_f32_e32 v23, v23, v70
	v_add_f32_e32 v7, v7, v71
	v_mul_f32_e32 v74, v22, v22
	v_mul_f32_e32 v75, v6, v6
	v_mul_f32_e32 v76, v23, v23
	v_mul_f32_e32 v77, v7, v7
	v_fma_f32 v74, v74, v73, v72
	v_fma_f32 v75, v75, v73, v72
	v_fma_f32 v76, v76, v73, v72
	v_fma_f32 v77, v77, v73, v72
	v_mul_f32_e32 v74, v74, v22
	v_mul_f32_e32 v75, v75, v6
	v_mul_f32_e32 v76, v76, v23
	v_mul_f32_e32 v77, v77, v7
	v_exp_f32_e32 v74, v74
	v_exp_f32_e32 v75, v75
	v_exp_f32_e32 v76, v76
	v_exp_f32_e32 v77, v77
	v_add_f32_e32 v74, 1.0, v74
	v_add_f32_e32 v75, 1.0, v75
	v_add_f32_e32 v76, 1.0, v76
	v_add_f32_e32 v77, 1.0, v77
	v_rcp_f32_e32 v74, v74
	v_rcp_f32_e32 v75, v75
	v_rcp_f32_e32 v76, v76
	v_rcp_f32_e32 v77, v77
	v_mul_f32_e32 v74, v22, v74
	v_mul_f32_e32 v75, v6, v75
	v_mul_f32_e32 v76, v23, v76
	v_mul_f32_e32 v77, v7, v77
	v_cvt_pk_bf16_f32 v74, v74, v74
	v_cvt_pk_bf16_f32 v75, v75, v75
	v_cvt_pk_bf16_f32 v76, v76, v76
	v_cvt_pk_bf16_f32 v77, v77, v77
	v_add_u32_e32 v78, 0x5400, v69
	global_store_short v78, v74, s[22:23]
	global_store_short v78, v75, s[22:23] offset:64
	v_add_u32_e32 v79, 0x5600, v69
	global_store_short v79, v76, s[22:23]
	global_store_short v79, v77, s[22:23] offset:64
	v_add_f32_e32 v24, v24, v70
	v_add_f32_e32 v8, v8, v71
	v_add_f32_e32 v25, v25, v70
	v_add_f32_e32 v9, v9, v71
	v_mul_f32_e32 v74, v24, v24
	v_mul_f32_e32 v75, v8, v8
	v_mul_f32_e32 v76, v25, v25
	v_mul_f32_e32 v77, v9, v9
	v_fma_f32 v74, v74, v73, v72
	v_fma_f32 v75, v75, v73, v72
	v_fma_f32 v76, v76, v73, v72
	v_fma_f32 v77, v77, v73, v72
	v_mul_f32_e32 v74, v74, v24
	v_mul_f32_e32 v75, v75, v8
	v_mul_f32_e32 v76, v76, v25
	v_mul_f32_e32 v77, v77, v9
	v_exp_f32_e32 v74, v74
	v_exp_f32_e32 v75, v75
	v_exp_f32_e32 v76, v76
	v_exp_f32_e32 v77, v77
	v_add_f32_e32 v74, 1.0, v74
	v_add_f32_e32 v75, 1.0, v75
	v_add_f32_e32 v76, 1.0, v76
	v_add_f32_e32 v77, 1.0, v77
	v_rcp_f32_e32 v74, v74
	v_rcp_f32_e32 v75, v75
	v_rcp_f32_e32 v76, v76
	v_rcp_f32_e32 v77, v77
	v_mul_f32_e32 v74, v24, v74
	v_mul_f32_e32 v75, v8, v75
	v_mul_f32_e32 v76, v25, v76
	v_mul_f32_e32 v77, v9, v77
	v_cvt_pk_bf16_f32 v74, v74, v74
	v_cvt_pk_bf16_f32 v75, v75, v75
	v_cvt_pk_bf16_f32 v76, v76, v76
	v_cvt_pk_bf16_f32 v77, v77, v77
	v_add_u32_e32 v78, 0x6000, v69
	global_store_short v78, v74, s[22:23]
	global_store_short v78, v75, s[22:23] offset:64
	v_add_u32_e32 v79, 0x6200, v69
	global_store_short v79, v76, s[22:23]
	global_store_short v79, v77, s[22:23] offset:64
	v_add_f32_e32 v26, v26, v70
	v_add_f32_e32 v10, v10, v71
	v_add_f32_e32 v27, v27, v70
	v_add_f32_e32 v11, v11, v71
	v_mul_f32_e32 v74, v26, v26
	v_mul_f32_e32 v75, v10, v10
	v_mul_f32_e32 v76, v27, v27
	v_mul_f32_e32 v77, v11, v11
	v_fma_f32 v74, v74, v73, v72
	v_fma_f32 v75, v75, v73, v72
	v_fma_f32 v76, v76, v73, v72
	v_fma_f32 v77, v77, v73, v72
	v_mul_f32_e32 v74, v74, v26
	v_mul_f32_e32 v75, v75, v10
	v_mul_f32_e32 v76, v76, v27
	v_mul_f32_e32 v77, v77, v11
	v_exp_f32_e32 v74, v74
	v_exp_f32_e32 v75, v75
	v_exp_f32_e32 v76, v76
	v_exp_f32_e32 v77, v77
	v_add_f32_e32 v74, 1.0, v74
	v_add_f32_e32 v75, 1.0, v75
	v_add_f32_e32 v76, 1.0, v76
	v_add_f32_e32 v77, 1.0, v77
	v_rcp_f32_e32 v74, v74
	v_rcp_f32_e32 v75, v75
	v_rcp_f32_e32 v76, v76
	v_rcp_f32_e32 v77, v77
	v_mul_f32_e32 v74, v26, v74
	v_mul_f32_e32 v75, v10, v75
	v_mul_f32_e32 v76, v27, v76
	v_mul_f32_e32 v77, v11, v77
	v_cvt_pk_bf16_f32 v74, v74, v74
	v_cvt_pk_bf16_f32 v75, v75, v75
	v_cvt_pk_bf16_f32 v76, v76, v76
	v_cvt_pk_bf16_f32 v77, v77, v77
	v_add_u32_e32 v78, 0x6400, v69
	global_store_short v78, v74, s[22:23]
	global_store_short v78, v75, s[22:23] offset:64
	v_add_u32_e32 v79, 0x6600, v69
	global_store_short v79, v76, s[22:23]
	global_store_short v79, v77, s[22:23] offset:64
	v_add_f32_e32 v28, v28, v70
	v_add_f32_e32 v12, v12, v71
	v_add_f32_e32 v29, v29, v70
	v_add_f32_e32 v13, v13, v71
	v_mul_f32_e32 v74, v28, v28
	v_mul_f32_e32 v75, v12, v12
	v_mul_f32_e32 v76, v29, v29
	v_mul_f32_e32 v77, v13, v13
	v_fma_f32 v74, v74, v73, v72
	v_fma_f32 v75, v75, v73, v72
	v_fma_f32 v76, v76, v73, v72
	v_fma_f32 v77, v77, v73, v72
	v_mul_f32_e32 v74, v74, v28
	v_mul_f32_e32 v75, v75, v12
	v_mul_f32_e32 v76, v76, v29
	v_mul_f32_e32 v77, v77, v13
	v_exp_f32_e32 v74, v74
	v_exp_f32_e32 v75, v75
	v_exp_f32_e32 v76, v76
	v_exp_f32_e32 v77, v77
	v_add_f32_e32 v74, 1.0, v74
	v_add_f32_e32 v75, 1.0, v75
	v_add_f32_e32 v76, 1.0, v76
	v_add_f32_e32 v77, 1.0, v77
	v_rcp_f32_e32 v74, v74
	v_rcp_f32_e32 v75, v75
	v_rcp_f32_e32 v76, v76
	v_rcp_f32_e32 v77, v77
	v_mul_f32_e32 v74, v28, v74
	v_mul_f32_e32 v75, v12, v75
	v_mul_f32_e32 v76, v29, v76
	v_mul_f32_e32 v77, v13, v77
	v_cvt_pk_bf16_f32 v74, v74, v74
	v_cvt_pk_bf16_f32 v75, v75, v75
	v_cvt_pk_bf16_f32 v76, v76, v76
	v_cvt_pk_bf16_f32 v77, v77, v77
	v_add_u32_e32 v78, 0x7000, v69
	global_store_short v78, v74, s[22:23]
	global_store_short v78, v75, s[22:23] offset:64
	v_add_u32_e32 v79, 0x7200, v69
	global_store_short v79, v76, s[22:23]
	global_store_short v79, v77, s[22:23] offset:64
	v_add_f32_e32 v30, v30, v70
	v_add_f32_e32 v14, v14, v71
	v_add_f32_e32 v31, v31, v70
	v_add_f32_e32 v15, v15, v71
	v_mul_f32_e32 v74, v30, v30
	v_mul_f32_e32 v75, v14, v14
	v_mul_f32_e32 v76, v31, v31
	v_mul_f32_e32 v77, v15, v15
	v_fma_f32 v74, v74, v73, v72
	v_fma_f32 v75, v75, v73, v72
	v_fma_f32 v76, v76, v73, v72
	v_fma_f32 v77, v77, v73, v72
	v_mul_f32_e32 v74, v74, v30
	v_mul_f32_e32 v75, v75, v14
	v_mul_f32_e32 v76, v76, v31
	v_mul_f32_e32 v77, v77, v15
	v_exp_f32_e32 v74, v74
	v_exp_f32_e32 v75, v75
	v_exp_f32_e32 v76, v76
	v_exp_f32_e32 v77, v77
	v_add_f32_e32 v74, 1.0, v74
	v_add_f32_e32 v75, 1.0, v75
	v_add_f32_e32 v76, 1.0, v76
	v_add_f32_e32 v77, 1.0, v77
	v_rcp_f32_e32 v74, v74
	v_rcp_f32_e32 v75, v75
	v_rcp_f32_e32 v76, v76
	v_rcp_f32_e32 v77, v77
	v_mul_f32_e32 v74, v30, v74
	v_mul_f32_e32 v75, v14, v75
	v_mul_f32_e32 v76, v31, v76
	v_mul_f32_e32 v77, v15, v77
	v_cvt_pk_bf16_f32 v74, v74, v74
	v_cvt_pk_bf16_f32 v75, v75, v75
	v_cvt_pk_bf16_f32 v76, v76, v76
	v_cvt_pk_bf16_f32 v77, v77, v77
	v_add_u32_e32 v78, 0x7400, v69
	global_store_short v78, v74, s[22:23]
	global_store_short v78, v75, s[22:23] offset:64
	v_add_u32_e32 v79, 0x7600, v69
	global_store_short v79, v76, s[22:23]
	global_store_short v79, v77, s[22:23] offset:64
	v_readlane_b32 s0, v254, 12
	v_readlane_b32 s1, v254, 13
	s_add_i32 s18, s18, s90
	s_nop 1
	s_xor_b64 s[4:5], s[4:5], s[0:1]
	s_cmp_gt_i32 s18, 63
	s_cbranch_scc1 .LBB0_1574
	s_branch .LBB0_1308
